# nt stores also for layer-0 FFN2 weights and WOT/WKV/WQS/WOS (all consumed late) in the prologue
# baseline (speedup 1.0000x reference)
.LBB0_27:
	s_waitcnt lgkmcnt(3)
	v_cvt_pk_bf16_f32 v10, v10, v11
	s_waitcnt lgkmcnt(2)
	v_cvt_pk_bf16_f32 v11, v12, v13
	s_waitcnt lgkmcnt(1)
	v_cvt_pk_bf16_f32 v12, v14, v15
	v_ashrrev_i32_e32 v14, 31, v18
	s_waitcnt lgkmcnt(0)
	v_cvt_pk_bf16_f32 v13, v16, v17
	v_mul_lo_u32 v16, s65, v18
	v_mul_lo_u32 v17, s64, v14
	v_mad_u64_u32 v[14:15], s[4:5], s64, v18, 0
	v_add3_u32 v15, v15, v17, v16
	v_lshl_add_u64 v[8:9], v[14:15], 1, v[8:9]
	s_cmp_lt_u32 s81, 0x840
	s_cbranch_scc1 .Lws7_def
	s_cmp_lt_u32 s81, 0x2100
	s_cbranch_scc1 .Lws7_nt
	s_cmp_lt_u32 s81, 0x2270
	s_cbranch_scc1 .Lws7_def
.Lws7_nt:
	global_store_dwordx4 v[8:9], v[10:13], off nt
	s_branch .Lws7_done

.LBB0_61:
	s_lshl_b64 s[6:7], s[6:7], 1
	s_add_u32 s4, s4, s6
	s_addc_u32 s5, s5, s7
	s_waitcnt lgkmcnt(0)
	v_cvt_pk_bf16_f32 v10, v10, v11
	v_cvt_pk_bf16_f32 v11, v12, v13
	v_cvt_pk_bf16_f32 v12, v14, v15
	v_ashrrev_i32_e32 v14, 31, v19
	v_lshl_add_u64 v[8:9], s[4:5], 0, v[2:3]
	v_cvt_pk_bf16_f32 v13, v16, v17
	v_mul_lo_u32 v16, s65, v19
	v_mul_lo_u32 v17, s64, v14
	v_mad_u64_u32 v[14:15], s[4:5], s64, v19, 0
	v_add3_u32 v15, v15, v17, v16
	v_lshl_add_u64 v[14:15], v[14:15], 1, v[8:9]
	s_cmp_lt_u32 s81, 0x840
	s_cbranch_scc1 .Lws6_def
	s_cmp_lt_u32 s81, 0x2100
	s_cbranch_scc1 .Lws6_nt
	s_cmp_lt_u32 s81, 0x2270
	s_cbranch_scc1 .Lws6_def
.Lws6_nt:
	global_store_dwordx4 v[14:15], v[10:13], off nt
	s_branch .Lws6_done

.LBB0_67:
	s_waitcnt lgkmcnt(3)
	v_cvt_pk_bf16_f32 v20, v10, v11
	v_ashrrev_i32_e32 v10, 31, v19
	v_mul_lo_u32 v11, s65, v19
	v_mul_lo_u32 v10, s64, v10
	v_mad_u64_u32 v[24:25], s[26:27], s64, v19, 0
	s_waitcnt lgkmcnt(2)
	v_cvt_pk_bf16_f32 v21, v12, v13
	s_waitcnt lgkmcnt(1)
	v_cvt_pk_bf16_f32 v22, v14, v15
	s_waitcnt lgkmcnt(0)
	v_cvt_pk_bf16_f32 v23, v16, v17
	v_add3_u32 v25, v25, v10, v11
	ds_read2_b32 v[10:11], v80 offset0:16 offset1:81
	ds_read2_b32 v[12:13], v80 offset0:146 offset1:211
	ds_read2_b32 v[14:15], v18 offset0:20 offset1:85
	ds_read2_b32 v[16:17], v18 offset0:150 offset1:215
	v_lshl_add_u64 v[24:25], v[24:25], 1, v[8:9]
	s_and_b64 vcc, exec, s[6:7]
	v_or_b32_e32 v19, s66, v82
	s_cmp_lt_u32 s81, 0x840
	s_cbranch_scc1 .Lws5_def
	s_cmp_lt_u32 s81, 0x2100
	s_cbranch_scc1 .Lws5_nt
	s_cmp_lt_u32 s81, 0x2270
	s_cbranch_scc1 .Lws5_def
.Lws5_nt:
	global_store_dwordx4 v[24:25], v[20:23], off nt
	s_branch .Lws5_done

.LBB0_73:
	s_waitcnt lgkmcnt(3)
	v_cvt_pk_bf16_f32 v20, v10, v11
	v_ashrrev_i32_e32 v10, 31, v19
	v_mul_lo_u32 v11, s65, v19
	v_mul_lo_u32 v10, s64, v10
	v_mad_u64_u32 v[24:25], s[26:27], s64, v19, 0
	s_waitcnt lgkmcnt(2)
	v_cvt_pk_bf16_f32 v21, v12, v13
	s_waitcnt lgkmcnt(1)
	v_cvt_pk_bf16_f32 v22, v14, v15
	s_waitcnt lgkmcnt(0)
	v_cvt_pk_bf16_f32 v23, v16, v17
	v_add3_u32 v25, v25, v10, v11
	ds_read2_b32 v[10:11], v80 offset0:24 offset1:89
	ds_read2_b32 v[12:13], v80 offset0:154 offset1:219
	ds_read2_b32 v[14:15], v18 offset0:28 offset1:93
	ds_read2_b32 v[16:17], v18 offset0:158 offset1:223
	v_lshl_add_u64 v[24:25], v[24:25], 1, v[8:9]
	s_and_b64 vcc, exec, s[6:7]
	v_or_b32_e32 v19, s66, v83
	s_cmp_lt_u32 s81, 0x840
	s_cbranch_scc1 .Lws4_def
	s_cmp_lt_u32 s81, 0x2100
	s_cbranch_scc1 .Lws4_nt
	s_cmp_lt_u32 s81, 0x2270
	s_cbranch_scc1 .Lws4_def

.LBB0_79:
	s_waitcnt lgkmcnt(3)
	v_cvt_pk_bf16_f32 v20, v10, v11
	v_ashrrev_i32_e32 v10, 31, v19
	v_mul_lo_u32 v11, s65, v19
	v_mul_lo_u32 v10, s64, v10
	v_mad_u64_u32 v[24:25], s[26:27], s64, v19, 0
	s_waitcnt lgkmcnt(2)
	v_cvt_pk_bf16_f32 v21, v12, v13
	s_waitcnt lgkmcnt(1)
	v_cvt_pk_bf16_f32 v22, v14, v15
	s_waitcnt lgkmcnt(0)
	v_cvt_pk_bf16_f32 v23, v16, v17
	v_add3_u32 v25, v25, v10, v11
	ds_read2_b32 v[10:11], v80 offset0:32 offset1:97
	ds_read2_b32 v[12:13], v80 offset0:162 offset1:227
	ds_read2_b32 v[14:15], v18 offset0:36 offset1:101
	ds_read2_b32 v[16:17], v18 offset0:166 offset1:231
	v_lshl_add_u64 v[24:25], v[24:25], 1, v[8:9]
	s_and_b64 vcc, exec, s[6:7]
	v_or_b32_e32 v19, s66, v84
	s_cmp_lt_u32 s81, 0x840
	s_cbranch_scc1 .Lws3_def
	s_cmp_lt_u32 s81, 0x2100
	s_cbranch_scc1 .Lws3_nt
	s_cmp_lt_u32 s81, 0x2270
	s_cbranch_scc1 .Lws3_def

.LBB0_85:
	s_waitcnt lgkmcnt(3)
	v_cvt_pk_bf16_f32 v20, v10, v11
	v_ashrrev_i32_e32 v10, 31, v19
	v_mul_lo_u32 v11, s65, v19
	v_mul_lo_u32 v10, s64, v10
	v_mad_u64_u32 v[24:25], s[26:27], s64, v19, 0
	s_waitcnt lgkmcnt(2)
	v_cvt_pk_bf16_f32 v21, v12, v13
	s_waitcnt lgkmcnt(1)
	v_cvt_pk_bf16_f32 v22, v14, v15
	s_waitcnt lgkmcnt(0)
	v_cvt_pk_bf16_f32 v23, v16, v17
	v_add3_u32 v25, v25, v10, v11
	ds_read2_b32 v[10:11], v80 offset0:40 offset1:105
	ds_read2_b32 v[12:13], v80 offset0:170 offset1:235
	ds_read2_b32 v[14:15], v18 offset0:44 offset1:109
	ds_read2_b32 v[16:17], v18 offset0:174 offset1:239
	v_lshl_add_u64 v[24:25], v[24:25], 1, v[8:9]
	s_and_b64 vcc, exec, s[6:7]
	v_or_b32_e32 v19, s66, v85
	s_cmp_lt_u32 s81, 0x840
	s_cbranch_scc1 .Lws2_def
	s_cmp_lt_u32 s81, 0x2100
	s_cbranch_scc1 .Lws2_nt
	s_cmp_lt_u32 s81, 0x2270
	s_cbranch_scc1 .Lws2_def

.LBB0_91:
	s_waitcnt lgkmcnt(3)
	v_cvt_pk_bf16_f32 v20, v10, v11
	v_ashrrev_i32_e32 v10, 31, v19
	v_mul_lo_u32 v11, s65, v19
	v_mul_lo_u32 v10, s64, v10
	v_mad_u64_u32 v[24:25], s[26:27], s64, v19, 0
	s_waitcnt lgkmcnt(2)
	v_cvt_pk_bf16_f32 v21, v12, v13
	s_waitcnt lgkmcnt(1)
	v_cvt_pk_bf16_f32 v22, v14, v15
	s_waitcnt lgkmcnt(0)
	v_cvt_pk_bf16_f32 v23, v16, v17
	v_add3_u32 v25, v25, v10, v11
	ds_read2_b32 v[10:11], v80 offset0:48 offset1:113
	ds_read2_b32 v[12:13], v80 offset0:178 offset1:243
	ds_read2_b32 v[14:15], v18 offset0:52 offset1:117
	ds_read2_b32 v[16:17], v18 offset0:182 offset1:247
	v_lshl_add_u64 v[24:25], v[24:25], 1, v[8:9]
	s_and_b64 vcc, exec, s[6:7]
	v_or_b32_e32 v19, s66, v86
	s_cmp_lt_u32 s81, 0x840
	s_cbranch_scc1 .Lws1_def
	s_cmp_lt_u32 s81, 0x2100
	s_cbranch_scc1 .Lws1_nt
	s_cmp_lt_u32 s81, 0x2270
	s_cbranch_scc1 .Lws1_def

.LBB0_97:
	s_waitcnt lgkmcnt(3)
	v_cvt_pk_bf16_f32 v20, v10, v11
	v_ashrrev_i32_e32 v10, 31, v19
	v_mul_lo_u32 v11, s65, v19
	v_mul_lo_u32 v10, s64, v10
	v_mad_u64_u32 v[24:25], s[26:27], s64, v19, 0
	s_waitcnt lgkmcnt(2)
	v_cvt_pk_bf16_f32 v21, v12, v13
	s_waitcnt lgkmcnt(1)
	v_cvt_pk_bf16_f32 v22, v14, v15
	s_waitcnt lgkmcnt(0)
	v_cvt_pk_bf16_f32 v23, v16, v17
	v_add3_u32 v25, v25, v10, v11
	ds_read2_b32 v[10:11], v80 offset0:56 offset1:121
	ds_read2_b32 v[12:13], v80 offset0:186 offset1:251
	ds_read2_b32 v[14:15], v18 offset0:60 offset1:125
	ds_read2_b32 v[16:17], v18 offset0:190 offset1:255
	v_lshl_add_u64 v[18:19], v[24:25], 1, v[8:9]
	s_cmp_lt_u32 s81, 0x840
	s_cbranch_scc1 .Lws0_def
	s_cmp_lt_u32 s81, 0x2100
	s_cbranch_scc1 .Lws0_nt
	s_cmp_lt_u32 s81, 0x2270
	s_cbranch_scc1 .Lws0_def
.Lws0_nt:
	global_store_dwordx4 v[18:19], v[20:23], off nt
	s_branch .Lws0_done
